# P5 and P8 epilogue stores also sc0 sc1 nt
# baseline (speedup 1.0000x reference)
;     __device__ __forceinline__ void operator()(const f32x4 (&acc)[2][2][4][2], const Unit& u, int wr, int wc, int fr, int fq) const {
;         const int row0 = u.pm * BM + wr * 64 + fr, col0 = u.pn * 256 + wc * 32 + 8 * fq;
;         const float* gp = gate + (size_t)(u.pm >> 3) * 6144 + col0;
;         f32x4 gq[2][2];
; #pragma unroll
;         for (int bj = 0; bj < 2; ++bj) { gq[bj][0] = *(const f32x4*)(gp + bj * HALF); gq[bj][1] = *(const f32x4*)(gp + bj * HALF + 4); }
.LBB0_485:
	s_ashr_i32 s33, s48, 3
	s_mul_hi_i32 s41, s33, 0x6000
	s_mulk_i32 s33, 0x6000
	v_lshl_or_b32 v128, s81, 8, v168
	s_add_u32 s50, s49, s33
	s_addc_u32 s51, s56, s41
	v_ashrrev_i32_e32 v129, 31, v128
	v_lshl_add_u64 v[132:133], v[128:129], 2, s[50:51]
	global_load_dwordx4 v[140:143], v[132:133], off
	global_load_dwordx4 v[136:139], v[132:133], off offset:16
	v_lshl_add_u32 v130, s48, 8, v166
	v_ashrrev_i32_e32 v131, 31, v130
	v_or_b32_e32 v134, 16, v130
	v_or_b32_e32 v160, 32, v130
	v_or_b32_e32 v162, 48, v130
	v_lshlrev_b64 v[130:131], 11, v[130:131]
	v_ashrrev_i32_e32 v135, 31, v134
	v_ashrrev_i32_e32 v161, 31, v160
	v_lshlrev_b64 v[164:165], 1, v[128:129]
	v_ashrrev_i32_e32 v163, 31, v162
	v_lshl_add_u64 v[128:129], s[18:19], 0, v[130:131]
	v_lshlrev_b64 v[130:131], 11, v[134:135]
	v_lshlrev_b64 v[134:135], 11, v[160:161]
	v_lshlrev_b64 v[160:161], 11, v[162:163]
	v_lshl_add_u64 v[172:173], v[128:129], 0, v[164:165]
	v_lshl_add_u64 v[162:163], s[18:19], 0, v[130:131]
	v_lshl_add_u64 v[176:177], s[18:19], 0, v[134:135]
	global_load_dwordx4 v[128:131], v[132:133], off offset:528
	s_nop 0
	global_load_dwordx4 v[132:135], v[132:133], off offset:512
	v_lshl_add_u64 v[178:179], v[162:163], 0, v[164:165]
	v_lshl_add_u64 v[160:161], s[18:19], 0, v[160:161]
	v_lshl_add_u64 v[176:177], v[176:177], 0, v[164:165]
	v_lshl_add_u64 v[160:161], v[160:161], 0, v[164:165]
	v_add_co_u32_e32 v180, vcc, s67, v172
	v_lshl_add_u64 v[162:163], v[172:173], 0, s[0:1]
	s_nop 0
	v_addc_co_u32_e32 v181, vcc, 0, v173, vcc
	v_lshl_add_u64 v[164:165], v[172:173], 0, s[12:13]
	s_waitcnt vmcnt(0)
; __device__ __forceinline__ unsigned cvt_pk_bf16(float lo, float hi) { unsigned r; asm volatile("v_cvt_pk_bf16_f32 %0, %1, %2" : "=v"(r) : "v"(lo), "v"(hi)); return r; }
;     __device__ __forceinline__ void operator()(const f32x4 (&acc)[2][2][4][2], const Unit& u, int wr, int wc, int fr, int fq) const {
;     ...
; #pragma unroll
;         for (int bj = 0; bj < 2; ++bj) { const f32x4 g0 = gq[bj][0], g1 = gq[bj][1];
; #pragma unroll
;             for (int ai = 0; ai < 2; ++ai)
; #pragma unroll
;                 for (int m = 0; m < 4; ++m) { const f32x4 v0 = acc[ai][bj][m][0] * g0, v1 = acc[ai][bj][m][1] * g1;
;                     u32x4 w; w.x = cvt_pk_bf16(v0[0], v0[1]); w.y = cvt_pk_bf16(v0[2], v0[3]); w.z = cvt_pk_bf16(v1[0], v1[1]); w.w = cvt_pk_bf16(v1[2], v1[3]);
;                     *(u32x4*)(out + (size_t)(row0 + ai * HALF + m * 16) * 1024 + col0 + bj * HALF) = w; } }
	v_pk_mul_f32 v[124:125], v[124:125], v[140:141]
	v_pk_mul_f32 v[184:185], v[80:81], v[136:137]
	v_cvt_pk_bf16_f32 v80, v124, v125
	v_pk_mul_f32 v[126:127], v[126:127], v[142:143]
	v_pk_mul_f32 v[122:123], v[122:123], v[138:139]
	v_pk_mul_f32 v[120:121], v[120:121], v[136:137]
	v_pk_mul_f32 v[116:117], v[116:117], v[140:141]
	v_pk_mul_f32 v[182:183], v[82:83], v[138:139]
	v_cvt_pk_bf16_f32 v81, v126, v127
	v_cvt_pk_bf16_f32 v82, v120, v121
	v_cvt_pk_bf16_f32 v83, v122, v123
	global_store_dwordx4 v[172:173], v[80:83], off sc0 sc1 nt
	v_pk_mul_f32 v[118:119], v[118:119], v[142:143]
	v_pk_mul_f32 v[114:115], v[114:115], v[138:139]
	v_cvt_pk_bf16_f32 v80, v116, v117
	v_pk_mul_f32 v[112:113], v[112:113], v[136:137]
	v_pk_mul_f32 v[108:109], v[108:109], v[140:141]
	v_cvt_pk_bf16_f32 v81, v118, v119
	v_cvt_pk_bf16_f32 v82, v112, v113
	v_cvt_pk_bf16_f32 v83, v114, v115
	global_store_dwordx4 v[178:179], v[80:83], off sc0 sc1 nt
	v_pk_mul_f32 v[110:111], v[110:111], v[142:143]
	v_pk_mul_f32 v[106:107], v[106:107], v[138:139]
	v_cvt_pk_bf16_f32 v80, v108, v109
	v_pk_mul_f32 v[104:105], v[104:105], v[136:137]
	v_pk_mul_f32 v[100:101], v[100:101], v[140:141]
	v_cvt_pk_bf16_f32 v81, v110, v111
	v_cvt_pk_bf16_f32 v82, v104, v105
	v_cvt_pk_bf16_f32 v83, v106, v107
	global_store_dwordx4 v[176:177], v[80:83], off sc0 sc1 nt
	v_pk_mul_f32 v[102:103], v[102:103], v[142:143]
	v_pk_mul_f32 v[98:99], v[98:99], v[138:139]
	v_cvt_pk_bf16_f32 v80, v100, v101
	v_pk_mul_f32 v[96:97], v[96:97], v[136:137]
	v_pk_mul_f32 v[92:93], v[92:93], v[140:141]
	v_pk_mul_f32 v[84:85], v[84:85], v[140:141]
	v_cvt_pk_bf16_f32 v81, v102, v103
	v_cvt_pk_bf16_f32 v82, v96, v97
	v_cvt_pk_bf16_f32 v83, v98, v99
	global_store_dwordx4 v[160:161], v[80:83], off sc0 sc1 nt
	v_pk_mul_f32 v[94:95], v[94:95], v[142:143]
	v_pk_mul_f32 v[90:91], v[90:91], v[138:139]
	v_cvt_pk_bf16_f32 v80, v92, v93
	v_pk_mul_f32 v[88:89], v[88:89], v[136:137]
	v_cvt_pk_bf16_f32 v81, v94, v95
	v_pk_mul_f32 v[86:87], v[86:87], v[142:143]
	v_cvt_pk_bf16_f32 v82, v88, v89
	v_cvt_pk_bf16_f32 v83, v90, v91
	global_store_dwordx4 v[180:181], v[80:83], off sc0 sc1 nt
	v_pk_mul_f32 v[78:79], v[78:79], v[142:143]
	v_pk_mul_f32 v[76:77], v[76:77], v[140:141]
	v_cvt_pk_bf16_f32 v80, v84, v85
	v_add_co_u32_e32 v84, vcc, s72, v172
	v_cvt_pk_bf16_f32 v81, v86, v87
	v_cvt_pk_bf16_f32 v82, v184, v185
	v_cvt_pk_bf16_f32 v83, v182, v183
	v_pk_mul_f32 v[62:63], v[62:63], v[142:143]
	s_nop 0
	v_addc_co_u32_e32 v85, vcc, 0, v173, vcc
	global_store_dwordx4 v[84:85], v[80:83], off sc0 sc1 nt
	v_pk_mul_f32 v[60:61], v[60:61], v[140:141]
	v_pk_mul_f32 v[64:65], v[64:65], v[128:129]
	v_pk_mul_f32 v[80:81], v[74:75], v[138:139]
	v_pk_mul_f32 v[74:75], v[72:73], v[136:137]
	v_cvt_pk_bf16_f32 v72, v76, v77
	v_cvt_pk_bf16_f32 v73, v78, v79
	v_add_co_u32_e32 v78, vcc, s73, v172
	v_cvt_pk_bf16_f32 v74, v74, v75
	v_cvt_pk_bf16_f32 v75, v80, v81
	v_pk_mul_f32 v[54:55], v[54:55], v[134:135]
	s_nop 0
	v_addc_co_u32_e32 v79, vcc, 0, v173, vcc
	global_store_dwordx4 v[78:79], v[72:75], off sc0 sc1 nt
	v_pk_mul_f32 v[52:53], v[52:53], v[132:133]
	v_pk_mul_f32 v[46:47], v[46:47], v[134:135]
	v_pk_mul_f32 v[72:73], v[58:59], v[138:139]
	v_pk_mul_f32 v[58:59], v[56:57], v[136:137]
	v_cvt_pk_bf16_f32 v56, v60, v61
	v_cvt_pk_bf16_f32 v57, v62, v63
	v_add_co_u32_e32 v62, vcc, s80, v172
	v_cvt_pk_bf16_f32 v58, v58, v59
	v_cvt_pk_bf16_f32 v59, v72, v73
	v_pk_mul_f32 v[44:45], v[44:45], v[132:133]
	s_nop 0
	v_addc_co_u32_e32 v63, vcc, 0, v173, vcc
	global_store_dwordx4 v[62:63], v[56:59], off sc0 sc1 nt
	v_pk_mul_f32 v[62:63], v[66:67], v[130:131]
	v_pk_mul_f32 v[38:39], v[38:39], v[134:135]
	v_pk_mul_f32 v[56:57], v[68:69], v[132:133]
	v_pk_mul_f32 v[58:59], v[70:71], v[134:135]
	v_cvt_pk_bf16_f32 v56, v56, v57
	v_pk_mul_f32 v[36:37], v[36:37], v[132:133]
	v_cvt_pk_bf16_f32 v57, v58, v59
	v_cvt_pk_bf16_f32 v58, v64, v65
	v_cvt_pk_bf16_f32 v59, v62, v63
	global_store_dwordx4 v[172:173], v[56:59], off offset:256 sc0 sc1 nt
	v_pk_mul_f32 v[30:31], v[30:31], v[134:135]
	v_pk_mul_f32 v[28:29], v[28:29], v[132:133]
	v_pk_mul_f32 v[56:57], v[50:51], v[130:131]
	v_pk_mul_f32 v[50:51], v[48:49], v[128:129]
	v_cvt_pk_bf16_f32 v48, v52, v53
	v_cvt_pk_bf16_f32 v49, v54, v55
	v_pk_mul_f32 v[22:23], v[22:23], v[134:135]
	v_cvt_pk_bf16_f32 v50, v50, v51
	v_cvt_pk_bf16_f32 v51, v56, v57
	global_store_dwordx4 v[178:179], v[48:51], off offset:256 sc0 sc1 nt
	v_pk_mul_f32 v[20:21], v[20:21], v[132:133]
	v_lshl_add_u64 v[76:77], v[172:173], 0, s[14:15]
	v_pk_mul_f32 v[48:49], v[42:43], v[130:131]
	v_pk_mul_f32 v[42:43], v[40:41], v[128:129]
	v_cvt_pk_bf16_f32 v40, v44, v45
	v_cvt_pk_bf16_f32 v41, v46, v47
	v_pk_mul_f32 v[14:15], v[14:15], v[134:135]
	v_cvt_pk_bf16_f32 v42, v42, v43
	v_cvt_pk_bf16_f32 v43, v48, v49
	global_store_dwordx4 v[176:177], v[40:43], off offset:256 sc0 sc1 nt
	v_pk_mul_f32 v[12:13], v[12:13], v[132:133]
	v_lshl_add_u64 v[60:61], v[172:173], 0, s[16:17]
	v_pk_mul_f32 v[40:41], v[34:35], v[130:131]
	v_pk_mul_f32 v[34:35], v[32:33], v[128:129]
	v_cvt_pk_bf16_f32 v32, v36, v37
	v_cvt_pk_bf16_f32 v33, v38, v39
	s_andn2_b64 vcc, exec, s[2:3]
	v_cvt_pk_bf16_f32 v34, v34, v35
	v_cvt_pk_bf16_f32 v35, v40, v41
	global_store_dwordx4 v[160:161], v[32:35], off offset:256 sc0 sc1 nt
	s_mov_b64 s[2:3], -1
	v_pk_mul_f32 v[6:7], v[6:7], v[134:135]
	v_pk_mul_f32 v[32:33], v[26:27], v[130:131]
	v_pk_mul_f32 v[26:27], v[24:25], v[128:129]
	v_cvt_pk_bf16_f32 v24, v28, v29
	v_cvt_pk_bf16_f32 v25, v30, v31
	v_pk_mul_f32 v[4:5], v[4:5], v[132:133]
	v_cvt_pk_bf16_f32 v26, v26, v27
	v_cvt_pk_bf16_f32 v27, v32, v33
	global_store_dwordx4 v[162:163], v[24:27], off offset:256 sc0 sc1 nt
	s_nop 1
	v_pk_mul_f32 v[24:25], v[18:19], v[130:131]
	v_pk_mul_f32 v[18:19], v[16:17], v[128:129]
	v_cvt_pk_bf16_f32 v16, v20, v21
	v_cvt_pk_bf16_f32 v17, v22, v23
	s_nop 0
	v_cvt_pk_bf16_f32 v18, v18, v19
	v_cvt_pk_bf16_f32 v19, v24, v25
	global_store_dwordx4 v[164:165], v[16:19], off offset:256 sc0 sc1 nt
	s_nop 1
	v_pk_mul_f32 v[16:17], v[10:11], v[130:131]
	v_pk_mul_f32 v[10:11], v[8:9], v[128:129]
	v_cvt_pk_bf16_f32 v8, v12, v13
	v_cvt_pk_bf16_f32 v9, v14, v15
	s_nop 0
	v_cvt_pk_bf16_f32 v10, v10, v11
	v_cvt_pk_bf16_f32 v11, v16, v17
	global_store_dwordx4 v[76:77], v[8:11], off offset:256 sc0 sc1 nt
	s_nop 1
	v_pk_mul_f32 v[8:9], v[2:3], v[130:131]
	v_pk_mul_f32 v[2:3], v[0:1], v[128:129]
	v_cvt_pk_bf16_f32 v0, v4, v5
	v_cvt_pk_bf16_f32 v1, v6, v7
	s_nop 0
	v_cvt_pk_bf16_f32 v2, v2, v3
	v_cvt_pk_bf16_f32 v3, v8, v9
	global_store_dwordx4 v[60:61], v[0:3], off offset:256 sc0 sc1 nt
	s_cbranch_vccnz .LBB0_474
	s_andn2_b64 vcc, exec, s[6:7]
	s_cbranch_vccnz .LBB0_473
	s_barrier
	s_branch .LBB0_473

;     __device__ __forceinline__ void operator()(const f32x4 (&acc)[2][2][4][2], const Unit& u, int wr, int wc, int fr, int fq) const {
;         const int row0 = u.pm * BM + wr * 64 + fr, col0 = u.pn * 256 + wc * 32 + 8 * fq;
;         const float* gp = gate + (size_t)(u.pm >> 3) * 6144 + col0;
;         f32x4 gq[2][2];
; #pragma unroll
;         for (int bj = 0; bj < 2; ++bj) { gq[bj][0] = *(const f32x4*)(gp + bj * HALF); gq[bj][1] = *(const f32x4*)(gp + bj * HALF + 4); }
.LBB0_688:
	s_ashr_i32 s33, s58, 3
	s_mul_hi_i32 s37, s33, 0x6000
	s_mulk_i32 s33, 0x6000
	v_lshl_or_b32 v128, s59, 8, v168
	s_add_u32 s36, s44, s33
	s_addc_u32 s37, s45, s37
	v_ashrrev_i32_e32 v129, 31, v128
	v_lshl_add_u64 v[132:133], v[128:129], 2, s[36:37]
	global_load_dwordx4 v[140:143], v[132:133], off
	global_load_dwordx4 v[136:139], v[132:133], off offset:16
	v_lshl_add_u32 v130, s58, 8, v166
	v_ashrrev_i32_e32 v131, 31, v130
	v_or_b32_e32 v134, 16, v130
	v_or_b32_e32 v160, 32, v130
	v_or_b32_e32 v162, 48, v130
	v_lshlrev_b64 v[130:131], 11, v[130:131]
	v_ashrrev_i32_e32 v135, 31, v134
	v_ashrrev_i32_e32 v161, 31, v160
	v_lshlrev_b64 v[164:165], 1, v[128:129]
	v_ashrrev_i32_e32 v163, 31, v162
	v_lshl_add_u64 v[128:129], s[20:21], 0, v[130:131]
	v_lshlrev_b64 v[130:131], 11, v[134:135]
	v_lshlrev_b64 v[134:135], 11, v[160:161]
	v_lshlrev_b64 v[160:161], 11, v[162:163]
	v_lshl_add_u64 v[172:173], v[128:129], 0, v[164:165]
	v_lshl_add_u64 v[162:163], s[20:21], 0, v[130:131]
	v_lshl_add_u64 v[176:177], s[20:21], 0, v[134:135]
	global_load_dwordx4 v[128:131], v[132:133], off offset:528
	s_nop 0
	global_load_dwordx4 v[132:135], v[132:133], off offset:512
	v_lshl_add_u64 v[178:179], v[162:163], 0, v[164:165]
	v_lshl_add_u64 v[160:161], s[20:21], 0, v[160:161]
	v_lshl_add_u64 v[176:177], v[176:177], 0, v[164:165]
	v_lshl_add_u64 v[160:161], v[160:161], 0, v[164:165]
	v_add_co_u32_e32 v180, vcc, s52, v172
	v_lshl_add_u64 v[162:163], v[172:173], 0, s[10:11]
	s_nop 0
	v_addc_co_u32_e32 v181, vcc, 0, v173, vcc
	v_lshl_add_u64 v[164:165], v[172:173], 0, s[12:13]
	s_waitcnt vmcnt(0)
; __device__ __forceinline__ unsigned cvt_pk_bf16(float lo, float hi) { unsigned r; asm volatile("v_cvt_pk_bf16_f32 %0, %1, %2" : "=v"(r) : "v"(lo), "v"(hi)); return r; }
;     __device__ __forceinline__ void operator()(const f32x4 (&acc)[2][2][4][2], const Unit& u, int wr, int wc, int fr, int fq) const {
;     ...
; #pragma unroll
;         for (int bj = 0; bj < 2; ++bj) { const f32x4 g0 = gq[bj][0], g1 = gq[bj][1];
; #pragma unroll
;             for (int ai = 0; ai < 2; ++ai)
; #pragma unroll
;                 for (int m = 0; m < 4; ++m) { const f32x4 v0 = acc[ai][bj][m][0] * g0, v1 = acc[ai][bj][m][1] * g1;
;                     u32x4 w; w.x = cvt_pk_bf16(v0[0], v0[1]); w.y = cvt_pk_bf16(v0[2], v0[3]); w.z = cvt_pk_bf16(v1[0], v1[1]); w.w = cvt_pk_bf16(v1[2], v1[3]);
;                     *(u32x4*)(out + (size_t)(row0 + ai * HALF + m * 16) * 1024 + col0 + bj * HALF) = w; } }
	v_pk_mul_f32 v[124:125], v[124:125], v[140:141]
	v_pk_mul_f32 v[184:185], v[80:81], v[136:137]
	v_cvt_pk_bf16_f32 v80, v124, v125
	v_pk_mul_f32 v[126:127], v[126:127], v[142:143]
	v_pk_mul_f32 v[122:123], v[122:123], v[138:139]
	v_pk_mul_f32 v[120:121], v[120:121], v[136:137]
	v_pk_mul_f32 v[116:117], v[116:117], v[140:141]
	v_pk_mul_f32 v[182:183], v[82:83], v[138:139]
	v_cvt_pk_bf16_f32 v81, v126, v127
	v_cvt_pk_bf16_f32 v82, v120, v121
	v_cvt_pk_bf16_f32 v83, v122, v123
	global_store_dwordx4 v[172:173], v[80:83], off sc0 sc1 nt
	v_pk_mul_f32 v[118:119], v[118:119], v[142:143]
	v_pk_mul_f32 v[114:115], v[114:115], v[138:139]
	v_cvt_pk_bf16_f32 v80, v116, v117
	v_pk_mul_f32 v[112:113], v[112:113], v[136:137]
	v_pk_mul_f32 v[108:109], v[108:109], v[140:141]
	v_cvt_pk_bf16_f32 v81, v118, v119
	v_cvt_pk_bf16_f32 v82, v112, v113
	v_cvt_pk_bf16_f32 v83, v114, v115
	global_store_dwordx4 v[178:179], v[80:83], off sc0 sc1 nt
	v_pk_mul_f32 v[110:111], v[110:111], v[142:143]
	v_pk_mul_f32 v[106:107], v[106:107], v[138:139]
	v_cvt_pk_bf16_f32 v80, v108, v109
	v_pk_mul_f32 v[104:105], v[104:105], v[136:137]
	v_pk_mul_f32 v[100:101], v[100:101], v[140:141]
	v_cvt_pk_bf16_f32 v81, v110, v111
	v_cvt_pk_bf16_f32 v82, v104, v105
	v_cvt_pk_bf16_f32 v83, v106, v107
	global_store_dwordx4 v[176:177], v[80:83], off sc0 sc1 nt
	v_pk_mul_f32 v[102:103], v[102:103], v[142:143]
	v_pk_mul_f32 v[98:99], v[98:99], v[138:139]
	v_cvt_pk_bf16_f32 v80, v100, v101
	v_pk_mul_f32 v[96:97], v[96:97], v[136:137]
	v_pk_mul_f32 v[92:93], v[92:93], v[140:141]
	v_pk_mul_f32 v[84:85], v[84:85], v[140:141]
	v_cvt_pk_bf16_f32 v81, v102, v103
	v_cvt_pk_bf16_f32 v82, v96, v97
	v_cvt_pk_bf16_f32 v83, v98, v99
	global_store_dwordx4 v[160:161], v[80:83], off sc0 sc1 nt
	v_pk_mul_f32 v[94:95], v[94:95], v[142:143]
	v_pk_mul_f32 v[90:91], v[90:91], v[138:139]
	v_cvt_pk_bf16_f32 v80, v92, v93
	v_pk_mul_f32 v[88:89], v[88:89], v[136:137]
	v_cvt_pk_bf16_f32 v81, v94, v95
	v_pk_mul_f32 v[86:87], v[86:87], v[142:143]
	v_cvt_pk_bf16_f32 v82, v88, v89
	v_cvt_pk_bf16_f32 v83, v90, v91
	global_store_dwordx4 v[180:181], v[80:83], off sc0 sc1 nt
	v_pk_mul_f32 v[78:79], v[78:79], v[142:143]
	v_pk_mul_f32 v[76:77], v[76:77], v[140:141]
	v_cvt_pk_bf16_f32 v80, v84, v85
	v_add_co_u32_e32 v84, vcc, s53, v172
	v_cvt_pk_bf16_f32 v81, v86, v87
	v_cvt_pk_bf16_f32 v82, v184, v185
	v_cvt_pk_bf16_f32 v83, v182, v183
	v_pk_mul_f32 v[62:63], v[62:63], v[142:143]
	s_nop 0
	v_addc_co_u32_e32 v85, vcc, 0, v173, vcc
	global_store_dwordx4 v[84:85], v[80:83], off sc0 sc1 nt
	v_pk_mul_f32 v[60:61], v[60:61], v[140:141]
	v_pk_mul_f32 v[64:65], v[64:65], v[128:129]
	v_pk_mul_f32 v[80:81], v[74:75], v[138:139]
	v_pk_mul_f32 v[74:75], v[72:73], v[136:137]
	v_cvt_pk_bf16_f32 v72, v76, v77
	v_cvt_pk_bf16_f32 v73, v78, v79
	v_add_co_u32_e32 v78, vcc, s54, v172
	v_cvt_pk_bf16_f32 v74, v74, v75
	v_cvt_pk_bf16_f32 v75, v80, v81
	v_pk_mul_f32 v[54:55], v[54:55], v[134:135]
	s_nop 0
	v_addc_co_u32_e32 v79, vcc, 0, v173, vcc
	global_store_dwordx4 v[78:79], v[72:75], off sc0 sc1 nt
	v_pk_mul_f32 v[52:53], v[52:53], v[132:133]
	v_pk_mul_f32 v[46:47], v[46:47], v[134:135]
	v_pk_mul_f32 v[72:73], v[58:59], v[138:139]
	v_pk_mul_f32 v[58:59], v[56:57], v[136:137]
	v_cvt_pk_bf16_f32 v56, v60, v61
	v_cvt_pk_bf16_f32 v57, v62, v63
	v_add_co_u32_e32 v62, vcc, s55, v172
	v_cvt_pk_bf16_f32 v58, v58, v59
	v_cvt_pk_bf16_f32 v59, v72, v73
	v_pk_mul_f32 v[44:45], v[44:45], v[132:133]
	s_nop 0
	v_addc_co_u32_e32 v63, vcc, 0, v173, vcc
	global_store_dwordx4 v[62:63], v[56:59], off sc0 sc1 nt
	v_pk_mul_f32 v[62:63], v[66:67], v[130:131]
	v_pk_mul_f32 v[38:39], v[38:39], v[134:135]
	v_pk_mul_f32 v[56:57], v[68:69], v[132:133]
	v_pk_mul_f32 v[58:59], v[70:71], v[134:135]
	v_cvt_pk_bf16_f32 v56, v56, v57
	v_pk_mul_f32 v[36:37], v[36:37], v[132:133]
	v_cvt_pk_bf16_f32 v57, v58, v59
	v_cvt_pk_bf16_f32 v58, v64, v65
	v_cvt_pk_bf16_f32 v59, v62, v63
	global_store_dwordx4 v[172:173], v[56:59], off offset:256 sc0 sc1 nt
	v_pk_mul_f32 v[30:31], v[30:31], v[134:135]
	v_pk_mul_f32 v[28:29], v[28:29], v[132:133]
	v_pk_mul_f32 v[56:57], v[50:51], v[130:131]
	v_pk_mul_f32 v[50:51], v[48:49], v[128:129]
	v_cvt_pk_bf16_f32 v48, v52, v53
	v_cvt_pk_bf16_f32 v49, v54, v55
	v_pk_mul_f32 v[22:23], v[22:23], v[134:135]
	v_cvt_pk_bf16_f32 v50, v50, v51
	v_cvt_pk_bf16_f32 v51, v56, v57
	global_store_dwordx4 v[178:179], v[48:51], off offset:256 sc0 sc1 nt
	v_pk_mul_f32 v[20:21], v[20:21], v[132:133]
	v_lshl_add_u64 v[76:77], v[172:173], 0, s[14:15]
	v_pk_mul_f32 v[48:49], v[42:43], v[130:131]
	v_pk_mul_f32 v[42:43], v[40:41], v[128:129]
	v_cvt_pk_bf16_f32 v40, v44, v45
	v_cvt_pk_bf16_f32 v41, v46, v47
	v_pk_mul_f32 v[14:15], v[14:15], v[134:135]
	v_cvt_pk_bf16_f32 v42, v42, v43
	v_cvt_pk_bf16_f32 v43, v48, v49
	global_store_dwordx4 v[176:177], v[40:43], off offset:256 sc0 sc1 nt
	v_pk_mul_f32 v[12:13], v[12:13], v[132:133]
	v_lshl_add_u64 v[60:61], v[172:173], 0, s[16:17]
	v_pk_mul_f32 v[40:41], v[34:35], v[130:131]
	v_pk_mul_f32 v[34:35], v[32:33], v[128:129]
	v_cvt_pk_bf16_f32 v32, v36, v37
	v_cvt_pk_bf16_f32 v33, v38, v39
	s_and_b64 vcc, exec, s[2:3]
	v_cvt_pk_bf16_f32 v34, v34, v35
	v_cvt_pk_bf16_f32 v35, v40, v41
	global_store_dwordx4 v[160:161], v[32:35], off offset:256 sc0 sc1 nt
	s_mov_b64 s[2:3], -1
	v_pk_mul_f32 v[6:7], v[6:7], v[134:135]
	v_pk_mul_f32 v[32:33], v[26:27], v[130:131]
	v_pk_mul_f32 v[26:27], v[24:25], v[128:129]
	v_cvt_pk_bf16_f32 v24, v28, v29
	v_cvt_pk_bf16_f32 v25, v30, v31
	v_pk_mul_f32 v[4:5], v[4:5], v[132:133]
	v_cvt_pk_bf16_f32 v26, v26, v27
	v_cvt_pk_bf16_f32 v27, v32, v33
	global_store_dwordx4 v[162:163], v[24:27], off offset:256 sc0 sc1 nt
	s_nop 1
	v_pk_mul_f32 v[24:25], v[18:19], v[130:131]
	v_pk_mul_f32 v[18:19], v[16:17], v[128:129]
	v_cvt_pk_bf16_f32 v16, v20, v21
	v_cvt_pk_bf16_f32 v17, v22, v23
	s_nop 0
	v_cvt_pk_bf16_f32 v18, v18, v19
	v_cvt_pk_bf16_f32 v19, v24, v25
	global_store_dwordx4 v[164:165], v[16:19], off offset:256 sc0 sc1 nt
	s_nop 1
	v_pk_mul_f32 v[16:17], v[10:11], v[130:131]
	v_pk_mul_f32 v[10:11], v[8:9], v[128:129]
	v_cvt_pk_bf16_f32 v8, v12, v13
	v_cvt_pk_bf16_f32 v9, v14, v15
	s_nop 0
	v_cvt_pk_bf16_f32 v10, v10, v11
	v_cvt_pk_bf16_f32 v11, v16, v17
	global_store_dwordx4 v[76:77], v[8:11], off offset:256 sc0 sc1 nt
	s_nop 1
	v_pk_mul_f32 v[8:9], v[2:3], v[130:131]
	v_pk_mul_f32 v[2:3], v[0:1], v[128:129]
	v_cvt_pk_bf16_f32 v0, v4, v5
	v_cvt_pk_bf16_f32 v1, v6, v7
	s_nop 0
	v_cvt_pk_bf16_f32 v2, v2, v3
	v_cvt_pk_bf16_f32 v3, v8, v9
	global_store_dwordx4 v[60:61], v[0:3], off offset:256 sc0 sc1 nt
	s_cbranch_vccnz .LBB0_673
	s_andn2_b64 vcc, exec, s[0:1]
	s_cbranch_vccnz .LBB0_672
	s_barrier
	s_branch .LBB0_672
